# adds static s_setprio 1 for the four full conv waves (0-3) during the SSD conv segment
# baseline (speedup 1.0000x reference)
; __device__ __forceinline__ float bflo(unsigned u) { return __uint_as_float(u << 16); }
; __device__ __forceinline__ float bfhi(unsigned u) { return __uint_as_float(u & 0xffff0000u); }
; __device__ __forceinline__ unsigned short f2bf(float f) { return (unsigned short)(cvt_pk_bf16(f, 0.f) & 0xffffu); }
; __device__ __forceinline__ float siluf_(float v) { return v * __builtin_amdgcn_rcpf(1.0f + __expf(-v)); }
; #define SSD_ISSUE_DT(c_) do { const int c__ = (c_); const float* dp = dtraw + (rowbase + (size_t)c__ * 128 + lane) * 32 + head; dtn0 = dp[0]; dtn1 = dp[64 * 32]; } while (0)
; __device__ __forceinline__ void ssd_item(const Params& p, LAS unsigned char* lds, int bl, int head, int dry) {
;     ...
;         __syncthreads();
; #pragma unroll
;         for (int r = 0; r < 16; ++r) { const int row = (r & 3) + 8 * (r >> 2) + rsub; SB[(pt * 32 + row) * SLD + nt * 32 + cl] = f2bf(accS[r]); }
;         { const bf16_t* zp = proj + (r0 + ti_d * 32 + cl) * PLD + COL_Z + head * 64 + pc_d * 32 + rsub;
; #pragma unroll
;           for (int g4 = 0; g4 < 4; ++g4) zr[g4] = *(const u32x2*)(zp + 8 * g4); }
;         SSD_ISSUE_DT(c + 1 < 32 ? c + 1 : 31);
;         __builtin_amdgcn_sched_barrier(0);
;         if (cact) {
;             if (c == 0 && rg == 0) { raw[0] = (u32x2){0u, 0u}; raw[1] = (u32x2){0u, 0u}; raw[2] = (u32x2){0u, 0u}; }
; #pragma unroll
;             for (int seg = 0; seg < 4; ++seg) {
;                 float val[8][4];
; #pragma unroll
;                 for (int j = 0; j < 8; ++j) { const int i = seg * 8 + j;
;                     const u32x2 x0 = raw[i], x1 = raw[i + 1], x2 = raw[i + 2], x3 = raw[i + 3];
;                     float v0 = cbv[0] + cw0[0] * bflo(x0.x) + cw1[0] * bflo(x1.x) + cw2[0] * bflo(x2.x) + cw3[0] * bflo(x3.x);
;                     float v1 = cbv[1] + cw0[1] * bfhi(x0.x) + cw1[1] * bfhi(x1.x) + cw2[1] * bfhi(x2.x) + cw3[1] * bfhi(x3.x);
;                     float v2 = cbv[2] + cw0[2] * bflo(x0.y) + cw1[2] * bflo(x1.y) + cw2[2] * bflo(x2.y) + cw3[2] * bflo(x3.y);
;                     float v3 = cbv[3] + cw0[3] * bfhi(x0.y) + cw1[3] * bfhi(x1.y) + cw2[3] * bfhi(x2.y) + cw3[3] * bfhi(x3.y);
;                     val[j][0] = siluf_(v0); val[j][1] = siluf_(v1); val[j][2] = siluf_(v2); val[j][3] = siluf_(v3); }
.LBB0_224:
	s_waitcnt lgkmcnt(0)
	s_barrier
	v_cvt_pk_bf16_f32 v16, v0, v185
	ds_write_b16 v186, v16
	v_cvt_pk_bf16_f32 v16, v1, v185
	ds_write_b16 v186, v16 offset:272
	v_cvt_pk_bf16_f32 v16, v2, v185
	ds_write_b16 v186, v16 offset:544
	v_cvt_pk_bf16_f32 v16, v3, v185
	ds_write_b16 v186, v16 offset:816
	v_cvt_pk_bf16_f32 v16, v4, v185
	ds_write_b16 v186, v16 offset:2176
	v_cvt_pk_bf16_f32 v16, v5, v185
	ds_write_b16 v186, v16 offset:2448
	v_cvt_pk_bf16_f32 v16, v6, v185
	ds_write_b16 v186, v16 offset:2720
	v_cvt_pk_bf16_f32 v16, v7, v185
	ds_write_b16 v186, v16 offset:2992
	v_cvt_pk_bf16_f32 v16, v8, v185
	ds_write_b16 v186, v16 offset:4352
	v_cvt_pk_bf16_f32 v16, v9, v185
	ds_write_b16 v186, v16 offset:4624
	v_cvt_pk_bf16_f32 v16, v10, v185
	ds_write_b16 v186, v16 offset:4896
	v_cvt_pk_bf16_f32 v16, v11, v185
	ds_write_b16 v186, v16 offset:5168
	v_cvt_pk_bf16_f32 v16, v12, v185
	s_lshl_b32 s0, s58, 7
	ds_write_b16 v186, v16 offset:6528
	v_cvt_pk_bf16_f32 v16, v13, v185
	s_bitcmp1_b32 s58, 0
	ds_write_b16 v186, v16 offset:6800
	v_cvt_pk_bf16_f32 v16, v14, v185
	s_cselect_b32 s1, 0x600, 0
	ds_write_b16 v186, v16 offset:7072
	v_cvt_pk_bf16_f32 v16, v15, v185
	s_or_b32 s36, s54, s0
	s_mov_b32 s37, s55
	ds_write_b16 v186, v16 offset:7344
	v_lshl_add_u64 v[16:17], v[72:73], 0, s[36:37]
	s_add_i32 s63, s1, 0
	v_mad_u64_u32 v[18:19], s[0:1], v16, s33, v[74:75]
	s_add_i32 s62, s58, 1
	s_add_i32 s63, s63, 0x22000
	v_mov_b32_e32 v16, v19
	s_lshl_b32 s2, s62, 7
	v_mad_u64_u32 v[16:17], s[0:1], v17, s33, v[16:17]
	s_cmp_eq_u32 s58, 31
	s_cselect_b64 s[0:1], -1, 0
	s_and_b64 s[56:57], s[0:1], exec
	s_cselect_b32 s2, 0xf80, s2
	v_mov_b32_e32 v19, v16
	v_lshl_add_u64 v[16:17], v[70:71], 0, s[2:3]
	v_lshlrev_b64 v[16:17], 7, v[16:17]
	v_lshl_add_u64 v[16:17], s[52:53], 0, v[16:17]
	global_load_dwordx2 v[104:105], v[18:19], off
	global_load_dwordx2 v[98:99], v[18:19], off offset:16
	global_load_dwordx2 v[96:97], v[18:19], off offset:32
	global_load_dwordx2 v[90:91], v[18:19], off offset:48
	global_load_dword v157, v[16:17], off
	v_add_co_u32_e32 v16, vcc, 0x2000, v16
	s_nop 1
	v_addc_co_u32_e32 v17, vcc, 0, v17, vcc
	global_load_dword v156, v[16:17], off
	v_mov_b32_e32 v16, 0
	s_and_saveexec_b64 s[56:57], s[40:41]
	s_cbranch_execz .LBB0_242
	s_cmp_lt_u32 s98, 4
	s_cbranch_scc0 .Lprio_skip
	s_setprio 1
.Lprio_skip:
	v_or_b32_e32 v16, s58, v166
	v_cmp_eq_u32_e32 vcc, 0, v16
	s_waitcnt vmcnt(37)
	v_and_b32_e32 v30, 0xffff0000, v148
	v_and_b32_e32 v34, 0xffff0000, v149
	v_cndmask_b32_e64 v21, v150, 0, vcc
	v_cndmask_b32_e64 v19, v152, 0, vcc
	v_lshlrev_b32_e32 v22, 16, v21
	v_and_b32_e32 v21, 0xffff0000, v21
	v_cndmask_b32_e64 v17, v154, 0, vcc
	v_fma_f32 v21, v49, v21, v65
	v_and_b32_e32 v24, 0xffff0000, v19
	v_fmac_f32_e32 v21, v53, v24
	v_and_b32_e32 v26, 0xffff0000, v17
	v_fmac_f32_e32 v21, v57, v26
	v_cndmask_b32_e64 v18, v153, 0, vcc
	v_fmac_f32_e32 v21, v61, v30
	v_lshlrev_b32_e32 v28, 16, v18
	v_and_b32_e32 v33, 0xffff0000, v18
	v_mul_f32_e32 v18, 0xbfb8aa3b, v21
	v_exp_f32_e32 v18, v18
	v_cndmask_b32_e64 v20, v151, 0, vcc
	v_lshlrev_b32_e32 v25, 16, v17
	v_lshlrev_b32_e32 v17, 16, v20
	v_fma_f32 v27, v50, v17, v66
	v_and_b32_e32 v17, 0xffff0000, v20
	v_add_f32_e32 v18, 1.0, v18
	v_cndmask_b32_e64 v16, v155, 0, vcc
	v_fma_f32 v20, v51, v17, v67
	v_rcp_f32_e32 v18, v18
	v_lshlrev_b32_e32 v31, 16, v16
	v_fmac_f32_e32 v20, v55, v33
	v_and_b32_e32 v16, 0xffff0000, v16
	v_fmac_f32_e32 v20, v59, v16
	v_fmac_f32_e32 v20, v63, v34
	v_lshlrev_b32_e32 v23, 16, v19
	v_mul_f32_e32 v19, v21, v18
	v_mul_f32_e32 v21, 0xbfb8aa3b, v20
	v_exp_f32_e32 v21, v21
	v_fma_f32 v22, v48, v22, v64
	v_fmac_f32_e32 v22, v52, v23
	v_fmac_f32_e32 v22, v56, v25
	v_add_f32_e32 v21, 1.0, v21
	v_rcp_f32_e32 v21, v21
	v_lshlrev_b32_e32 v29, 16, v148
	v_fmac_f32_e32 v22, v60, v29
	v_mul_f32_e32 v17, 0xbfb8aa3b, v22
	v_mul_f32_e32 v20, v20, v21
	v_fma_f32 v21, v48, v23, v64
	v_exp_f32_e32 v17, v17
	v_fmac_f32_e32 v21, v52, v25
	v_fmac_f32_e32 v21, v56, v29
	s_waitcnt vmcnt(36)
	v_lshlrev_b32_e32 v35, 16, v146
	v_fmac_f32_e32 v21, v60, v35
	v_mul_f32_e32 v23, 0xbfb8aa3b, v21
	v_add_f32_e32 v17, 1.0, v17
	v_exp_f32_e32 v23, v23
	v_rcp_f32_e32 v17, v17
	v_and_b32_e32 v36, 0xffff0000, v146
	v_fmac_f32_e32 v27, v54, v28
	v_add_f32_e32 v23, 1.0, v23
	v_mul_f32_e32 v17, v22, v17
	v_fma_f32 v22, v49, v24, v65
	v_rcp_f32_e32 v23, v23
	v_fmac_f32_e32 v22, v53, v26
	v_fmac_f32_e32 v22, v57, v30
	v_fmac_f32_e32 v22, v61, v36
	v_mul_f32_e32 v21, v21, v23
	v_mul_f32_e32 v23, 0xbfb8aa3b, v22
	v_exp_f32_e32 v23, v23
	v_fmac_f32_e32 v27, v58, v31
	v_lshlrev_b32_e32 v32, 16, v149
	v_fmac_f32_e32 v27, v62, v32
	v_add_f32_e32 v23, 1.0, v23
	v_mul_f32_e32 v18, 0xbfb8aa3b, v27
	v_fma_f32 v24, v50, v28, v66
	v_rcp_f32_e32 v23, v23
	v_exp_f32_e32 v18, v18
	v_fmac_f32_e32 v24, v54, v31
	v_fmac_f32_e32 v24, v58, v32
	v_lshlrev_b32_e32 v37, 16, v147
	v_fmac_f32_e32 v24, v62, v37
	v_mul_f32_e32 v23, v22, v23
	v_mul_f32_e32 v22, 0xbfb8aa3b, v24
	v_add_f32_e32 v18, 1.0, v18
	v_exp_f32_e32 v22, v22
	v_rcp_f32_e32 v18, v18
	v_fma_f32 v25, v48, v25, v64
	v_fmac_f32_e32 v25, v52, v29
	v_add_f32_e32 v22, 1.0, v22
	v_mul_f32_e32 v18, v27, v18
	v_fma_f32 v27, v51, v33, v67
	v_rcp_f32_e32 v22, v22
	v_fmac_f32_e32 v27, v55, v16
	v_fmac_f32_e32 v27, v59, v34
	v_and_b32_e32 v33, 0xffff0000, v147
	v_fmac_f32_e32 v27, v63, v33
	v_mul_f32_e32 v22, v24, v22
	v_mul_f32_e32 v24, 0xbfb8aa3b, v27
	v_exp_f32_e32 v24, v24
	v_fmac_f32_e32 v25, v56, v35
	s_waitcnt vmcnt(35)
; __device__ __forceinline__ float bflo(unsigned u) { return __uint_as_float(u << 16); }
; __device__ __forceinline__ float bfhi(unsigned u) { return __uint_as_float(u & 0xffff0000u); }
; __device__ __forceinline__ float siluf_(float v) { return v * __builtin_amdgcn_rcpf(1.0f + __expf(-v)); }
; __device__ __forceinline__ void ssd_item(const Params& p, LAS unsigned char* lds, int bl, int head, int dry) {
;     ...
;                 for (int j = 0; j < 8; ++j) { const int i = seg * 8 + j;
;                     const u32x2 x0 = raw[i], x1 = raw[i + 1], x2 = raw[i + 2], x3 = raw[i + 3];
;                     float v0 = cbv[0] + cw0[0] * bflo(x0.x) + cw1[0] * bflo(x1.x) + cw2[0] * bflo(x2.x) + cw3[0] * bflo(x3.x);
;                     float v1 = cbv[1] + cw0[1] * bfhi(x0.x) + cw1[1] * bfhi(x1.x) + cw2[1] * bfhi(x2.x) + cw3[1] * bfhi(x3.x);
;                     float v2 = cbv[2] + cw0[2] * bflo(x0.y) + cw1[2] * bflo(x1.y) + cw2[2] * bflo(x2.y) + cw3[2] * bflo(x3.y);
;                     float v3 = cbv[3] + cw0[3] * bfhi(x0.y) + cw1[3] * bfhi(x1.y) + cw2[3] * bfhi(x2.y) + cw3[3] * bfhi(x3.y);
;                     val[j][0] = siluf_(v0); val[j][1] = siluf_(v1); val[j][2] = siluf_(v2); val[j][3] = siluf_(v3); }
	v_lshlrev_b32_e32 v38, 16, v144
	v_fmac_f32_e32 v25, v60, v38
	v_add_f32_e32 v24, 1.0, v24
	v_rcp_f32_e32 v24, v24
	v_fma_f32 v26, v49, v26, v65
	v_fmac_f32_e32 v26, v53, v30
	v_fmac_f32_e32 v26, v57, v36
	v_mul_f32_e32 v24, v27, v24
	v_mul_f32_e32 v27, 0xbfb8aa3b, v25
	v_exp_f32_e32 v27, v27
	v_and_b32_e32 v39, 0xffff0000, v144
	v_fmac_f32_e32 v26, v61, v39
	v_fma_f32 v28, v50, v31, v66
	v_add_f32_e32 v27, 1.0, v27
	v_rcp_f32_e32 v27, v27
	v_fmac_f32_e32 v28, v54, v32
	v_fmac_f32_e32 v28, v58, v37
	v_lshlrev_b32_e32 v40, 16, v145
	v_mul_f32_e32 v25, v25, v27
	v_mul_f32_e32 v27, 0xbfb8aa3b, v26
	v_exp_f32_e32 v27, v27
	v_fmac_f32_e32 v28, v62, v40
	v_fma_f32 v16, v51, v16, v67
	v_fmac_f32_e32 v16, v55, v34
	v_add_f32_e32 v27, 1.0, v27
	v_rcp_f32_e32 v27, v27
	v_fmac_f32_e32 v16, v59, v33
	v_and_b32_e32 v41, 0xffff0000, v145
	v_fmac_f32_e32 v16, v63, v41
	v_mul_f32_e32 v27, v26, v27
	v_mul_f32_e32 v26, 0xbfb8aa3b, v28
	v_exp_f32_e32 v26, v26
	s_waitcnt vmcnt(34)
	v_lshlrev_b32_e32 v42, 16, v142
	v_fma_f32 v30, v49, v30, v65
	v_fmac_f32_e32 v30, v53, v36
	v_add_f32_e32 v26, 1.0, v26
	v_rcp_f32_e32 v26, v26
	v_fmac_f32_e32 v30, v57, v39
	v_and_b32_e32 v43, 0xffff0000, v142
	v_fmac_f32_e32 v30, v61, v43
	v_mul_f32_e32 v26, v28, v26
	v_mul_f32_e32 v28, 0xbfb8aa3b, v16
	v_exp_f32_e32 v28, v28
	v_fma_f32 v32, v50, v32, v66
	v_fmac_f32_e32 v32, v54, v37
	v_fmac_f32_e32 v32, v58, v40
	v_add_f32_e32 v28, 1.0, v28
	v_rcp_f32_e32 v28, v28
	v_lshlrev_b32_e32 v44, 16, v143
	v_fmac_f32_e32 v32, v62, v44
	v_fma_f32 v34, v51, v34, v67
	v_mul_f32_e32 v28, v16, v28
	v_fma_f32 v16, v48, v29, v64
	v_fmac_f32_e32 v16, v52, v35
	v_fmac_f32_e32 v16, v56, v38
	v_fmac_f32_e32 v16, v60, v42
	v_mul_f32_e32 v29, 0xbfb8aa3b, v16
	v_exp_f32_e32 v29, v29
	v_fmac_f32_e32 v34, v55, v33
	v_fmac_f32_e32 v34, v59, v41
	v_and_b32_e32 v45, 0xffff0000, v143
	v_add_f32_e32 v29, 1.0, v29
	v_rcp_f32_e32 v29, v29
	v_fmac_f32_e32 v34, v63, v45
	s_waitcnt vmcnt(33)
	v_lshlrev_b32_e32 v46, 16, v140
	v_and_b32_e32 v47, 0xffff0000, v140
	v_mul_f32_e32 v29, v16, v29
	v_mul_f32_e32 v16, 0xbfb8aa3b, v30
	v_exp_f32_e32 v16, v16
	v_lshlrev_b32_e32 v145, 16, v141
	v_and_b32_e32 v146, 0xffff0000, v141
	v_fma_f32 v141, v49, v39, v65
	v_add_f32_e32 v16, 1.0, v16
	v_rcp_f32_e32 v16, v16
	v_fmac_f32_e32 v141, v53, v43
	v_fmac_f32_e32 v141, v57, v47
	v_fma_f32 v143, v49, v43, v65
	v_mul_f32_e32 v31, v30, v16
	v_mul_f32_e32 v16, 0xbfb8aa3b, v32
	v_exp_f32_e32 v16, v16
	v_fmac_f32_e32 v143, v53, v47
	v_fma_f32 v147, v49, v47, v65
	v_fma_f32 v148, v50, v145, v66
	v_add_f32_e32 v16, 1.0, v16
	v_rcp_f32_e32 v16, v16
	s_nop 0
	v_mul_f32_e32 v30, v32, v16
	v_mul_f32_e32 v16, 0xbfb8aa3b, v34
	v_exp_f32_e32 v16, v16
	s_nop 0
	v_add_f32_e32 v16, 1.0, v16
	v_rcp_f32_e32 v16, v16
	s_nop 0
	v_mul_f32_e32 v32, v34, v16
	v_fma_f32 v16, v48, v35, v64
	v_fmac_f32_e32 v16, v52, v38
	v_fmac_f32_e32 v16, v56, v42
	v_fmac_f32_e32 v16, v60, v46
	v_fma_f32 v34, v49, v36, v65
	v_fma_f32 v36, v50, v37, v66
	v_fma_f32 v37, v51, v33, v67
	v_mul_f32_e32 v33, 0xbfb8aa3b, v16
	v_exp_f32_e32 v33, v33
	v_fmac_f32_e32 v34, v53, v39
	v_fmac_f32_e32 v34, v57, v43
	v_fmac_f32_e32 v34, v61, v47
	v_add_f32_e32 v33, 1.0, v33
	v_rcp_f32_e32 v33, v33
	v_fmac_f32_e32 v36, v54, v40
	v_fmac_f32_e32 v36, v58, v44
	v_fmac_f32_e32 v36, v62, v145
	v_mul_f32_e32 v33, v16, v33
	v_mul_f32_e32 v16, 0xbfb8aa3b, v34
	v_exp_f32_e32 v16, v16
	v_fmac_f32_e32 v37, v55, v41
	v_fmac_f32_e32 v37, v59, v45
	v_fmac_f32_e32 v37, v63, v146
	v_add_f32_e32 v16, 1.0, v16
	v_rcp_f32_e32 v16, v16
	v_fma_f32 v40, v50, v40, v66
	v_fmac_f32_e32 v40, v54, v44
	v_fmac_f32_e32 v40, v58, v145
	v_mul_f32_e32 v35, v34, v16
	v_mul_f32_e32 v16, 0xbfb8aa3b, v36
	v_exp_f32_e32 v16, v16
	v_fma_f32 v41, v51, v41, v67
	v_fmac_f32_e32 v41, v55, v45
	v_fmac_f32_e32 v41, v59, v146
	v_add_f32_e32 v16, 1.0, v16
	v_rcp_f32_e32 v16, v16
	s_waitcnt vmcnt(32)
	v_and_b32_e32 v39, 0xffff0000, v139
	v_fmac_f32_e32 v41, v63, v39
	v_fma_f32 v44, v50, v44, v66
	v_mul_f32_e32 v34, v36, v16
	v_mul_f32_e32 v16, 0xbfb8aa3b, v37
	v_exp_f32_e32 v16, v16
	v_lshlrev_b32_e32 v36, 16, v138
	v_fmac_f32_e32 v44, v54, v145
	v_fma_f32 v45, v51, v45, v67
	v_add_f32_e32 v16, 1.0, v16
	v_rcp_f32_e32 v16, v16
	v_fmac_f32_e32 v45, v55, v146
	v_fmac_f32_e32 v45, v59, v39
	s_waitcnt vmcnt(31)
; __device__ __forceinline__ unsigned cvt_pk_bf16(float lo, float hi) { unsigned r; asm volatile("v_cvt_pk_bf16_f32 %0, %1, %2" : "=v"(r) : "v"(lo), "v"(hi)); return r; }
; #define LAS __attribute__((address_space(3)))
; __device__ __forceinline__ float bflo(unsigned u) { return __uint_as_float(u << 16); }
; __device__ __forceinline__ float bfhi(unsigned u) { return __uint_as_float(u & 0xffff0000u); }
; __device__ __forceinline__ float siluf_(float v) { return v * __builtin_amdgcn_rcpf(1.0f + __expf(-v)); }
; __device__ __forceinline__ void ssd_item(const Params& p, LAS unsigned char* lds, int bl, int head, int dry) {
;     ...
;                 for (int j = 0; j < 8; ++j) { const int i = seg * 8 + j;
;                     const u32x2 x0 = raw[i], x1 = raw[i + 1], x2 = raw[i + 2], x3 = raw[i + 3];
;                     float v0 = cbv[0] + cw0[0] * bflo(x0.x) + cw1[0] * bflo(x1.x) + cw2[0] * bflo(x2.x) + cw3[0] * bflo(x3.x);
;                     float v1 = cbv[1] + cw0[1] * bfhi(x0.x) + cw1[1] * bfhi(x1.x) + cw2[1] * bfhi(x2.x) + cw3[1] * bfhi(x3.x);
;                     float v2 = cbv[2] + cw0[2] * bflo(x0.y) + cw1[2] * bflo(x1.y) + cw2[2] * bflo(x2.y) + cw3[2] * bflo(x3.y);
;                     float v3 = cbv[3] + cw0[3] * bfhi(x0.y) + cw1[3] * bfhi(x1.y) + cw2[3] * bfhi(x2.y) + cw3[3] * bfhi(x3.y);
;                     val[j][0] = siluf_(v0); val[j][1] = siluf_(v1); val[j][2] = siluf_(v2); val[j][3] = siluf_(v3); }
;                 const int lb = rg * 32 + seg * 8;
;                 if (kind != 0) { LAS bf16_t* rm = (kind == 1 ? BMm : CM) + lb * SLD + n4;
; #pragma unroll
;                     for (int j = 0; j < 8; ++j) { u32x2 o; o.x = cvt_pk_bf16(val[j][0], val[j][1]); o.y = cvt_pk_bf16(val[j][2], val[j][3]); *(LAS u32x2*)(rm + j * SLD) = o; } }
	v_and_b32_e32 v43, 0xffff0000, v137
	v_mul_f32_e32 v140, v37, v16
	v_fma_f32 v16, v48, v38, v64
	v_fmac_f32_e32 v16, v52, v42
	v_fmac_f32_e32 v16, v56, v46
	v_fmac_f32_e32 v16, v60, v36
	v_and_b32_e32 v37, 0xffff0000, v138
	v_mul_f32_e32 v138, 0xbfb8aa3b, v16
	v_exp_f32_e32 v138, v138
	v_fmac_f32_e32 v141, v61, v37
	v_lshlrev_b32_e32 v38, 16, v139
	v_fmac_f32_e32 v40, v62, v38
	v_add_f32_e32 v138, 1.0, v138
	v_rcp_f32_e32 v138, v138
	v_fmac_f32_e32 v143, v57, v37
	v_fmac_f32_e32 v44, v58, v38
	v_fmac_f32_e32 v45, v63, v43
	v_mul_f32_e32 v138, v16, v138
	v_mul_f32_e32 v16, 0xbfb8aa3b, v141
	v_exp_f32_e32 v16, v16
	v_fmac_f32_e32 v147, v53, v37
	v_fmac_f32_e32 v148, v54, v38
	v_fma_f32 v146, v51, v146, v67
	v_add_f32_e32 v16, 1.0, v16
	v_rcp_f32_e32 v16, v16
	v_fmac_f32_e32 v146, v55, v39
	v_fmac_f32_e32 v146, v59, v43
	s_waitcnt vmcnt(30)
	v_and_b32_e32 v47, 0xffff0000, v135
	v_mul_f32_e32 v141, v141, v16
	v_mul_f32_e32 v16, 0xbfb8aa3b, v40
	v_exp_f32_e32 v16, v16
	v_fmac_f32_e32 v146, v63, v47
	v_add_f32_e32 v16, 1.0, v16
	v_rcp_f32_e32 v16, v16
	s_nop 0
	v_mul_f32_e32 v139, v40, v16
	v_mul_f32_e32 v16, 0xbfb8aa3b, v41
	v_exp_f32_e32 v16, v16
	v_lshlrev_b32_e32 v40, 16, v136
	v_add_f32_e32 v16, 1.0, v16
	v_rcp_f32_e32 v16, v16
	s_nop 0
	v_mul_f32_e32 v142, v41, v16
	v_fma_f32 v16, v48, v42, v64
	v_fmac_f32_e32 v16, v52, v46
	v_fmac_f32_e32 v16, v56, v36
	v_fmac_f32_e32 v16, v60, v40
	v_and_b32_e32 v41, 0xffff0000, v136
	v_mul_f32_e32 v136, 0xbfb8aa3b, v16
	v_exp_f32_e32 v136, v136
	v_fmac_f32_e32 v143, v61, v41
	v_lshlrev_b32_e32 v42, 16, v137
	v_fmac_f32_e32 v44, v62, v42
	v_add_f32_e32 v136, 1.0, v136
	v_rcp_f32_e32 v136, v136
	v_fmac_f32_e32 v147, v57, v41
	v_fmac_f32_e32 v148, v58, v42
	v_mul_f32_e32 v136, v16, v136
	v_mul_f32_e32 v16, 0xbfb8aa3b, v143
	v_exp_f32_e32 v16, v16
	s_nop 0
	v_add_f32_e32 v16, 1.0, v16
	v_rcp_f32_e32 v16, v16
	s_nop 0
	v_mul_f32_e32 v143, v143, v16
	v_mul_f32_e32 v16, 0xbfb8aa3b, v44
	v_exp_f32_e32 v16, v16
	s_nop 0
	v_add_f32_e32 v16, 1.0, v16
	v_rcp_f32_e32 v16, v16
	s_nop 0
	v_mul_f32_e32 v137, v44, v16
	v_mul_f32_e32 v16, 0xbfb8aa3b, v45
	v_exp_f32_e32 v16, v16
	v_lshlrev_b32_e32 v44, 16, v134
	v_add_f32_e32 v16, 1.0, v16
	v_rcp_f32_e32 v16, v16
	s_nop 0
	v_mul_f32_e32 v144, v45, v16
	v_fma_f32 v16, v48, v46, v64
	v_fmac_f32_e32 v16, v52, v36
	v_fmac_f32_e32 v16, v56, v40
	v_fmac_f32_e32 v16, v60, v44
	v_and_b32_e32 v45, 0xffff0000, v134
	v_mul_f32_e32 v134, 0xbfb8aa3b, v16
	v_exp_f32_e32 v134, v134
	v_fmac_f32_e32 v147, v61, v45
	v_lshlrev_b32_e32 v46, 16, v135
	v_fmac_f32_e32 v148, v62, v46
	v_add_f32_e32 v134, 1.0, v134
	v_rcp_f32_e32 v134, v134
	s_nop 0
	v_mul_f32_e32 v134, v16, v134
	v_mul_f32_e32 v16, 0xbfb8aa3b, v147
	v_exp_f32_e32 v16, v16
	s_nop 0
	v_add_f32_e32 v16, 1.0, v16
	v_rcp_f32_e32 v16, v16
	s_nop 0
	v_mul_f32_e32 v145, v147, v16
	v_mul_f32_e32 v16, 0xbfb8aa3b, v148
	v_exp_f32_e32 v16, v16
	s_nop 0
	v_add_f32_e32 v16, 1.0, v16
	v_rcp_f32_e32 v16, v16
	s_nop 0
	v_mul_f32_e32 v135, v148, v16
	v_mul_f32_e32 v16, 0xbfb8aa3b, v146
	v_exp_f32_e32 v16, v16
	s_nop 0
	v_add_f32_e32 v16, 1.0, v16
	v_rcp_f32_e32 v16, v16
	s_nop 0
	v_mul_f32_e32 v146, v146, v16
	s_and_saveexec_b64 vcc, s[38:39]
	s_cbranch_execz .LBB0_227
	v_cvt_pk_bf16_f32 v148, v17, v19
	v_cvt_pk_bf16_f32 v149, v18, v20
	ds_write_b64 v187, v[148:149]
	v_cvt_pk_bf16_f32 v148, v21, v23
	v_cvt_pk_bf16_f32 v149, v22, v24
	ds_write_b64 v187, v[148:149] offset:272
	v_cvt_pk_bf16_f32 v148, v25, v27
	v_cvt_pk_bf16_f32 v149, v26, v28
	ds_write_b64 v187, v[148:149] offset:544
	v_cvt_pk_bf16_f32 v148, v29, v31
	v_cvt_pk_bf16_f32 v149, v30, v32
	ds_write_b64 v187, v[148:149] offset:816
	v_cvt_pk_bf16_f32 v148, v33, v35
	v_cvt_pk_bf16_f32 v149, v34, v140
	ds_write_b64 v187, v[148:149] offset:1088
	v_cvt_pk_bf16_f32 v148, v138, v141
	v_cvt_pk_bf16_f32 v149, v139, v142
	ds_write_b64 v187, v[148:149] offset:1360
	v_cvt_pk_bf16_f32 v148, v136, v143
	v_cvt_pk_bf16_f32 v149, v137, v144
	ds_write_b64 v187, v[148:149] offset:1632
	v_cvt_pk_bf16_f32 v148, v134, v145
	v_cvt_pk_bf16_f32 v149, v135, v146
	ds_write_b64 v187, v[148:149] offset:1904

.Lconv_skip:
	s_setprio 0
	v_add_u32_e32 v16, s2, v163
